# attention: step barrier moved up behind PV MFMA 13 (all LDS accesses of the step issued and retired), next step's first eight K fragments requested right behind it, last two PV MFMAs and the next-tile
# baseline (speedup 1.0000x reference)
; __device__ __forceinline__ void attn_phase(LAS unsigned char* lds, const bf16_t* __restrict__ Q, const bf16_t* __restrict__ KN, const bf16_t* __restrict__ KR,
;                                            const bf16_t* __restrict__ VT, bf16_t* AO, int vcu, int G, int tid, int lane, int wave) {
;     ...
;                 if (2 * t + 1 <= qc) {
;                     bf16x8 kf[12], kf2[12], vf[8], vf2[8], pa[4], pb2[4]; f32x16 a0, a1, b0, b1;
;                     attn_ldk(kf, kA);
;                     __builtin_amdgcn_sched_barrier(0);
;                     attn_qk(a0, a1, kf, qf);
;                     attn_ldk(kf2, kA + 64 * KP * 2);
;                     __builtin_amdgcn_sched_barrier(0);
;                     attn_qk(b0, b1, kf2, qf);
;                     attn_softmax(a0, a1, pa, o0, o1, m_run, l_run);
;                     attn_ldv(vf, vA);
;                     __builtin_amdgcn_sched_barrier(0);
;                     PREFETCH_NEXT();
;                     attn_ldv(vf2, vA + 128);
;                     __builtin_amdgcn_sched_barrier(0);
;                     attn_pv(vf, pa, o0, o1);
;                     attn_softmax(b0, b1, pb2, o0, o1, m_run, l_run);
;                     __builtin_amdgcn_sched_barrier(0);
;                     attn_pv(vf2, pb2, o0, o1);
.Lat_both_d:
	s_waitcnt vmcnt(5)
	s_waitcnt lgkmcnt(7)
	v_mfma_f32_32x32x16_bf16 v[34:49], v[138:141], v[114:117], v[98:113]
	ds_read_b128 v[138:141], v1 offset:6720
	s_waitcnt lgkmcnt(7)
	v_mfma_f32_32x32x16_bf16 v[34:49], v[142:145], v[118:121], v[34:49]
	ds_read_b128 v[142:145], v1 offset:6752
	s_waitcnt lgkmcnt(7)
	v_mfma_f32_32x32x16_bf16 v[34:49], v[146:149], v[122:125], v[34:49]
	ds_read_b128 v[146:149], v1 offset:6784
	s_waitcnt lgkmcnt(7)
	v_mfma_f32_32x32x16_bf16 v[34:49], v[150:153], v[126:129], v[34:49]
	ds_read_b128 v[150:153], v1 offset:6816
	s_waitcnt lgkmcnt(7)
	v_mfma_f32_32x32x16_bf16 v[34:49], v[154:157], v[130:133], v[34:49]
	ds_read_b128 v[154:157], v1 offset:13312
	s_waitcnt lgkmcnt(7)
	v_mfma_f32_32x32x16_bf16 v[34:49], v[158:161], v[134:137], v[34:49]
	ds_read_b128 v[158:161], v1 offset:19968
	s_cmp_lg_u32 s7, 0
	s_cbranch_scc1 .Lat_plain_A2
	s_waitcnt lgkmcnt(7)
	v_mfma_f32_32x32x16_bf16 v[50:65], v[162:165], v[114:117], v[98:113]
	ds_read_b128 v[162:165], v1 offset:13344
	s_waitcnt lgkmcnt(7)
	v_mfma_f32_32x32x16_bf16 v[50:65], v[166:169], v[118:121], v[50:65]
	ds_read_b128 v[166:169], v1 offset:20000
	s_nop 2
	v_exp_f32_e32 v34, v34
	v_exp_f32_e32 v35, v35
	v_exp_f32_e32 v36, v36
	v_exp_f32_e32 v37, v37
	s_waitcnt lgkmcnt(7)
	v_mfma_f32_32x32x16_bf16 v[50:65], v[138:141], v[122:125], v[50:65]
	ds_read_b128 v[138:141], v1 offset:13376
	v_exp_f32_e32 v38, v38
	v_exp_f32_e32 v39, v39
	v_exp_f32_e32 v40, v40
	s_waitcnt lgkmcnt(7)
	v_mfma_f32_32x32x16_bf16 v[50:65], v[142:145], v[126:129], v[50:65]
	ds_read_b128 v[142:145], v1 offset:20032
	v_exp_f32_e32 v41, v41
	v_exp_f32_e32 v42, v42
	v_exp_f32_e32 v43, v43
	s_waitcnt lgkmcnt(7)
	v_mfma_f32_32x32x16_bf16 v[50:65], v[146:149], v[130:133], v[50:65]
	ds_read_b128 v[146:149], v1 offset:13408
	v_exp_f32_e32 v44, v44
	v_exp_f32_e32 v45, v45
	v_exp_f32_e32 v46, v46
	s_waitcnt lgkmcnt(7)
	v_mfma_f32_32x32x16_bf16 v[50:65], v[150:153], v[134:137], v[50:65]
	ds_read_b128 v[150:153], v1 offset:20064
	v_exp_f32_e32 v47, v47
	v_exp_f32_e32 v48, v48
	v_exp_f32_e32 v49, v49
	s_waitcnt lgkmcnt(7)
	v_mfma_f32_32x32x16_bf16 v[66:81], v[154:157], v[114:117], v[98:113]
	ds_read_b128 v[154:157], v1 offset:13440
	s_waitcnt lgkmcnt(7)
	v_mfma_f32_32x32x16_bf16 v[82:97], v[158:161], v[114:117], v[98:113]
	ds_read_b128 v[158:161], v1 offset:20096
	s_nop 1
	v_exp_f32_e32 v50, v50
	v_exp_f32_e32 v51, v51
	v_exp_f32_e32 v52, v52
	v_exp_f32_e32 v53, v53
	s_waitcnt lgkmcnt(7)
	v_mfma_f32_32x32x16_bf16 v[66:81], v[162:165], v[118:121], v[66:81]
	ds_read_b128 v[162:165], v1 offset:13472
	v_exp_f32_e32 v54, v54
	v_exp_f32_e32 v55, v55
	v_exp_f32_e32 v56, v56
	s_waitcnt lgkmcnt(7)
	v_mfma_f32_32x32x16_bf16 v[82:97], v[166:169], v[118:121], v[82:97]
	ds_read_b128 v[166:169], v1 offset:20128
	v_exp_f32_e32 v57, v57
	v_exp_f32_e32 v58, v58
	v_exp_f32_e32 v59, v59
	s_waitcnt lgkmcnt(7)
	v_mfma_f32_32x32x16_bf16 v[66:81], v[138:141], v[122:125], v[66:81]
	ds_read_b128 v[170:173], v225 offset:26624
	v_exp_f32_e32 v60, v60
	v_exp_f32_e32 v61, v61
	v_exp_f32_e32 v62, v62
	s_waitcnt lgkmcnt(7)
	v_mfma_f32_32x32x16_bf16 v[82:97], v[142:145], v[122:125], v[82:97]
	ds_read_b128 v[174:177], v225 offset:35328
	v_exp_f32_e32 v63, v63
	v_exp_f32_e32 v64, v64
	v_exp_f32_e32 v65, v65
	s_waitcnt lgkmcnt(7)
	v_mfma_f32_32x32x16_bf16 v[66:81], v[146:149], v[126:129], v[66:81]
	ds_read_b128 v[178:181], v225 offset:26656
	v_add_f32_e32 v250, v34, v36
	v_add_f32_e32 v251, v35, v37
	v_add_f32_e32 v252, v50, v52
	v_add_f32_e32 v253, v51, v53
	v_add_f32_e32 v250, v250, v38
	v_add_f32_e32 v251, v251, v39
	s_waitcnt lgkmcnt(7)
	v_mfma_f32_32x32x16_bf16 v[82:97], v[150:153], v[126:129], v[82:97]
	ds_read_b128 v[182:185], v225 offset:35360
	v_add_f32_e32 v252, v252, v54
	v_add_f32_e32 v253, v253, v55
	v_add_f32_e32 v250, v250, v40
	v_add_f32_e32 v251, v251, v41
	v_add_f32_e32 v252, v252, v56
	s_waitcnt lgkmcnt(7)
	v_mfma_f32_32x32x16_bf16 v[66:81], v[154:157], v[130:133], v[66:81]
	ds_read_b128 v[186:189], v225 offset:26688
	v_add_f32_e32 v253, v253, v57
	v_add_f32_e32 v250, v250, v42
	v_add_f32_e32 v251, v251, v43
	v_add_f32_e32 v252, v252, v58
	v_add_f32_e32 v253, v253, v59
	s_waitcnt lgkmcnt(7)
	v_mfma_f32_32x32x16_bf16 v[82:97], v[158:161], v[130:133], v[82:97]
	ds_read_b128 v[190:193], v225 offset:35392
	v_add_f32_e32 v250, v250, v44
	v_add_f32_e32 v251, v251, v45
	v_add_f32_e32 v252, v252, v60
	v_add_f32_e32 v253, v253, v61
	v_add_f32_e32 v250, v250, v46
	s_waitcnt lgkmcnt(7)
	v_mfma_f32_32x32x16_bf16 v[66:81], v[162:165], v[134:137], v[66:81]
	v_add_f32_e32 v251, v251, v47
	v_add_f32_e32 v252, v252, v62
	v_add_f32_e32 v253, v253, v63
	v_add_f32_e32 v250, v250, v48
	v_add_f32_e32 v251, v251, v49
	s_waitcnt lgkmcnt(6)
	v_mfma_f32_32x32x16_bf16 v[82:97], v[166:169], v[134:137], v[82:97]
	v_add_f32_e32 v252, v252, v64
	v_add_f32_e32 v253, v253, v65
	v_add_f32_e32 v250, v250, v252
	v_add_f32_e32 v251, v251, v253
	v_add_f32_e32 v1, v250, v251
	s_mov_b32 s41, 0
	s_branch .Lat_sum_A2

; #define LAS __attribute__((address_space(3)))
; __device__ __forceinline__ void attn_phase(LAS unsigned char* lds, const bf16_t* __restrict__ Q, const bf16_t* __restrict__ KN, const bf16_t* __restrict__ KR,
;                                            const bf16_t* __restrict__ VT, bf16_t* AO, int vcu, int G, int tid, int lane, int wave) {
;     ...
;             for (int t = 0; t < NT2; ++t) {
;                 const bool more = (t + 1 < NT2);
;                 const LAS unsigned char* buf = lds + (t & 1) * BUF;
;                 const LAS unsigned char* kA = buf + (pr * KP + 8 * hi) * 2; const LAS unsigned char* vA = buf + KBUF + (r32 * VP + 8 * hi) * 2;
;                 if (2 * t + 1 <= qc) {
;                     bf16x8 kf[12], kf2[12], vf[8], vf2[8], pa[4], pb2[4]; f32x16 a0, a1, b0, b1;
;                     attn_ldk(kf, kA);
;     ...
;                 if (more) { LAS unsigned char* nb = lds + ((t + 1) & 1) * BUF;
;                     *(LAS u32x4*)(nb + kdst) = gk0; *(LAS u32x4*)(nb + kdst + 64 * KP * 2) = gk1; *(LAS u32x4*)(nb + rdst) = gr; *(LAS u32x4*)(nb + vdst) = gv0; *(LAS u32x4*)(nb + vdst + 128) = gv1; }
;                 __syncthreads();
;             }
.Lat_fast_B2:
	v_add_f32_e32 v227, v227, v1
	v_cvt_pk_bf16_f32 v66, v66, v67
	v_cvt_pk_bf16_f32 v67, v68, v69
	v_cvt_pk_bf16_f32 v68, v70, v71
	v_cvt_pk_bf16_f32 v69, v72, v73
	v_cvt_pk_bf16_f32 v74, v74, v75
	v_cvt_pk_bf16_f32 v75, v76, v77
	v_cvt_pk_bf16_f32 v76, v78, v79
	v_cvt_pk_bf16_f32 v77, v80, v81
	v_cvt_pk_bf16_f32 v82, v82, v83
	v_cvt_pk_bf16_f32 v83, v84, v85
	v_cvt_pk_bf16_f32 v84, v86, v87
	v_cvt_pk_bf16_f32 v85, v88, v89
	v_cvt_pk_bf16_f32 v90, v90, v91
	v_cvt_pk_bf16_f32 v91, v92, v93
	v_cvt_pk_bf16_f32 v92, v94, v95
	v_cvt_pk_bf16_f32 v93, v96, v97
	s_waitcnt lgkmcnt(5)
	v_mfma_f32_32x32x16_bf16 v[2:17], v[178:181], v[66:69], v[2:17]
	ds_read_b128 v[178:181], v225 offset:26848
	s_waitcnt vmcnt(0)
	v_add_u32_e32 v226, s38, v219
	ds_write_b128 v226, v[228:231]
	s_waitcnt lgkmcnt(6)
	v_mfma_f32_32x32x16_bf16 v[18:33], v[182:185], v[66:69], v[18:33]
	ds_read_b128 v[182:185], v225 offset:35552
	ds_write_b128 v226, v[232:235] offset:13312
	s_waitcnt lgkmcnt(7)
	v_mfma_f32_32x32x16_bf16 v[2:17], v[186:189], v[74:77], v[2:17]
	v_add_u32_e32 v226, s38, v220
	ds_write_b128 v226, v[236:239]
	s_waitcnt lgkmcnt(7)
	v_mfma_f32_32x32x16_bf16 v[18:33], v[190:193], v[74:77], v[18:33]
	v_add_u32_e32 v226, s38, v221
	ds_write_b128 v226, v[240:243] offset:26624
	s_waitcnt lgkmcnt(7)
	v_mfma_f32_32x32x16_bf16 v[2:17], v[170:173], v[82:85], v[2:17]
	ds_write_b128 v226, v[244:247] offset:26752
	s_waitcnt lgkmcnt(7)
	v_mfma_f32_32x32x16_bf16 v[18:33], v[174:177], v[82:85], v[18:33]
	s_waitcnt lgkmcnt(0)
	s_barrier
	s_mov_b32 s8, s39
	s_cmp_lt_u32 s8, s36
	s_cbranch_scc0 .Lat_e_join
	s_add_i32 s39, s8, 1
	s_bitcmp1_b32 s8, 0
	s_cselect_b32 s37, 0xac00, 0
	s_cselect_b32 s38, 0, 0xac00
	v_add_u32_e32 v1, s37, v222
	v_add_u32_e32 v225, s37, v223
	s_lshl_b32 s40, s8, 1
	s_cmp_lt_u32 s40, s33
	s_cbranch_scc0 .Lat_e_join
	ds_read_b128 v[138:141], v1
	ds_read_b128 v[142:145], v1 offset:32
	ds_read_b128 v[146:149], v1 offset:64
	ds_read_b128 v[150:153], v1 offset:96
	ds_read_b128 v[154:157], v1 offset:128
	ds_read_b128 v[158:161], v1 offset:160
	ds_read_b128 v[162:165], v1 offset:6656
	ds_read_b128 v[166:169], v1 offset:6688
.Lat_e_join:
	v_mfma_f32_32x32x16_bf16 v[2:17], v[178:181], v[90:93], v[2:17]
	v_mfma_f32_32x32x16_bf16 v[18:33], v[182:185], v[90:93], v[18:33]
	s_cmp_lt_u32 s8, s36
	s_cbranch_scc0 .Lat_e_exit
	s_cmp_lt_u32 s39, s36
	s_cbranch_scc0 .Lat_e_nopf
	s_mov_b32 s40, s39
	s_mov_b32 s41, 0
	s_lshl_b64 s[14:15], s[40:41], 17
	s_add_u32 s14, s10, s14
	s_addc_u32 s15, s11, s15
	global_load_dwordx4 v[228:231], v198, s[14:15]
	s_add_u32 s14, s14, 0x10000
	s_addc_u32 s15, s15, 0
	global_load_dwordx4 v[232:235], v198, s[14:15]
	s_lshl_b64 s[14:15], s[40:41], 13
	v_lshl_add_u64 v[250:251], v[208:209], 0, s[14:15]
	s_lshl_b64 s[14:15], s[40:41], 8
	v_lshl_add_u64 v[252:253], v[210:211], 0, s[14:15]
	global_load_dwordx4 v[236:239], v[250:251], off
	global_load_dwordx4 v[240:243], v[252:253], off
	global_load_dwordx4 v[244:247], v[252:253], off offset:128

; __device__ __forceinline__ void attn_phase(LAS unsigned char* lds, const bf16_t* __restrict__ Q, const bf16_t* __restrict__ KN, const bf16_t* __restrict__ KR,
;                                            const bf16_t* __restrict__ VT, bf16_t* AO, int vcu, int G, int tid, int lane, int wave) {
;     ...
;     for (int p = vcu; p < 512; p += G) {
.Lat_e_exit:
	s_branch .LBB0_532
